# placement experiment: FFN-in loop head at 16 mod 64, others 64-aligned
# speedup vs baseline: 1.0043x; 1.0043x over previous
; #define PG8_STAGE(bufoff, gbase, voff) do { _Pragma("unroll") for (int _i = 0; _i < 2; ++_i) \
;         __builtin_amdgcn_global_load_lds((const unsigned*)((const char*)(gbase) + (voff)[_i]), (LAS unsigned*)(lds + (bufoff) + ldsw + _i * 8192), 16, 0, 0); } while (0)
; #define PG8_WAIT_V(n) asm volatile("s_waitcnt vmcnt(" #n ")" ::: "memory")
; #define PG8_BAR __builtin_amdgcn_s_barrier()
; template <class Epi, class Sched>
; __device__ __forceinline__ void gemm_phase(LAS unsigned char* lds, const Gemm g, const Sched& S, const Epi& E) {
;     ...
;     PG8_WAIT_V(2); PG8_BAR;
;     PG8_STAGE(PG8_SB(1, 0), cB + kstep, voffB); PG8_STAGE(PG8_SA(1, 0), cA + kstep, voffA); PG8_STAGE(PG8_SB(1, 1), cB + hstepB + kstep, voffB);
;     PG8_WAIT_V(6); PG8_BAR;
;     for (;;) {
;         const bool has_next = S.next(ui + 1, nxt);
;         const char* nA = has_next ? (const char*)g.A + (size_t)nxt.pm * tstepA + (size_t)nxt.ka * 2 : cA; const char* nB = has_next ? (const char*)g.Bt + (size_t)nxt.pn * tstepB : cB;
;         for (int t = 0; t < nt; t += 2) {
.Lmy_rsfill_done:
	s_or_b64 exec, exec, s[100:101]
	s_mov_b32 s100, s54
	s_waitcnt lgkmcnt(0)
	s_barrier
	v_readlane_b32 s19, v253, 54
	s_branch .LBB0_134
	s_nop 0
	s_nop 0
	s_nop 0
	s_nop 0
	s_nop 0
	s_nop 0
	s_nop 0
	s_nop 0
	s_nop 0
	s_nop 0
	s_nop 0

; #define PG8_STAGE(bufoff, gbase, voff) do { _Pragma("unroll") for (int _i = 0; _i < 2; ++_i) \
;         __builtin_amdgcn_global_load_lds((const unsigned*)((const char*)(gbase) + (voff)[_i]), (LAS unsigned*)(lds + (bufoff) + ldsw + _i * 8192), 16, 0, 0); } while (0)
; #define PG8_WAIT_V(n) asm volatile("s_waitcnt vmcnt(" #n ")" ::: "memory")
; #define PG8_BAR __builtin_amdgcn_s_barrier()
; template <class Epi, class Sched>
; __device__ __forceinline__ void gemm_phase(LAS unsigned char* lds, const Gemm g, const Sched& S, const Epi& E) {
;     ...
;     f32x4 acc[2][2][4][2];
; #pragma unroll
;     for (int a = 0; a < 2; ++a)
; #pragma unroll
;         for (int b = 0; b < 2; ++b)
; #pragma unroll
;             for (int m = 0; m < 4; ++m)
; #pragma unroll
;                 for (int n = 0; n < 2; ++n) acc[a][b][m][n] = (f32x4){0.f, 0.f, 0.f, 0.f};
;     bf16x8 At[4][2], B0[2][2], B1[2][2];
;     const char* cA = (const char*)g.A + (size_t)cur.pm * tstepA + (size_t)cur.ka * 2; const char* cB = (const char*)g.Bt + (size_t)cur.pn * tstepB;
;     S.a_ready(cur);
;     PG8_STAGE(PG8_SB(0, 0), cB, voffB); PG8_STAGE(PG8_SB(0, 1), cB + hstepB, voffB); PG8_STAGE(PG8_SA(0, 0), cA, voffA); PG8_STAGE(PG8_SA(0, 1), cA + hstepA, voffA);
;     if (wr == 1) PG8_BAR;
;     PG8_WAIT_V(2); PG8_BAR;
;     PG8_STAGE(PG8_SB(1, 0), cB + kstep, voffB); PG8_STAGE(PG8_SA(1, 0), cA + kstep, voffA); PG8_STAGE(PG8_SB(1, 1), cB + hstepB + kstep, voffB);
;     PG8_WAIT_V(6); PG8_BAR;
.LBB0_267:
	v_lshl_add_u64 v[14:15], s[24:25], 0, v[4:5]
	v_mov_b32_e32 v3, v5
	v_and_b32_e32 v142, 15, v143
	v_and_b32_e32 v22, 48, v143
	v_lshlrev_b32_e32 v23, 2, v143
	v_lshl_add_u64 v[16:17], s[24:25], 0, v[2:3]
	s_and_b32 s48, s44, 3
	v_lshl_or_b32 v22, v142, 6, v22
	s_lshl_b32 s4, s47, 13
	v_and_b32_e32 v23, 32, v23
	s_add_i32 m0, s50, 0x18000
	v_lshl_add_u64 v[14:15], v[14:15], 0, s[36:37]
	v_lshl_add_u64 v[18:19], s[20:21], 0, v[4:5]
	v_bitop3_b32 v24, v22, s4, v23 bitop3:0xde
	s_lshl_b32 s4, s48, 12
	s_waitcnt vmcnt(2)
	s_barrier
	global_load_lds_dwordx4 v[14:15], off
	v_lshl_add_u64 v[14:15], v[16:17], 0, s[36:37]
	s_add_i32 m0, s50, 0x1a000
	s_add_i32 s54, s50, 0x8000
	s_add_i32 s55, s50, 0xa000
	v_lshl_add_u64 v[20:21], s[20:21], 0, v[2:3]
	v_bitop3_b32 v144, v22, s4, v23 bitop3:0xde
	global_load_lds_dwordx4 v[14:15], off
	v_lshl_add_u64 v[14:15], v[18:19], 0, s[36:37]
	s_mov_b32 m0, s54
	s_add_u32 s4, s24, 0x158080
	global_load_lds_dwordx4 v[14:15], off
	v_lshl_add_u64 v[14:15], v[20:21], 0, s[36:37]
	s_mov_b32 m0, s55
	s_addc_u32 s5, s25, 0
	global_load_lds_dwordx4 v[14:15], off
	s_add_i32 m0, s50, 0x1c000
	v_lshl_add_u64 v[14:15], s[4:5], 0, v[4:5]
	global_load_lds_dwordx4 v[14:15], off
	v_lshl_add_u64 v[14:15], s[4:5], 0, v[2:3]
	s_add_i32 m0, s50, 0x1e000
	s_movk_i32 s10, 0x1580
	global_load_lds_dwordx4 v[14:15], off
	v_lshrrev_b32_e32 v11, 1, v11
	v_mul_lo_u32 v10, v10, s10
	s_mov_b32 s22, 0x15800
	v_mad_u64_u32 v[10:11], s[4:5], v11, s22, v[10:11]
	v_or_b32_e32 v10, v10, v12
	v_add_lshl_u32 v134, v10, v13, 1
	v_lshrrev_b32_e32 v10, 1, v6
	v_mul_lo_u32 v6, v7, s10
	v_mad_u64_u32 v[6:7], s[4:5], v10, s22, v[6:7]
	s_waitcnt vmcnt(6)
	v_or_b32_e32 v6, v6, v8
	s_cmpk_lt_u32 s45, 0x100
	v_add_lshl_u32 v136, v6, v9, 1
	v_mov_b32_e32 v6, 0
	v_readlane_b32 s4, v254, 13
	s_cselect_b64 s[18:19], -1, 0
	v_mov_b32_e32 v135, v5
	v_mov_b32_e32 v137, v5
	s_mov_b32 s59, 0
	v_add_u32_e32 v145, 0, v24
	s_mov_b32 s10, s4
	v_readlane_b32 s46, v253, 61
	v_mov_b32_e32 v7, v6
	v_mov_b32_e32 v8, v6
	v_mov_b32_e32 v9, v6
	v_mov_b32_e32 v10, v6
	v_mov_b32_e32 v11, v6
	v_mov_b32_e32 v12, v6
	v_mov_b32_e32 v13, v6
	v_mov_b32_e32 v14, v6
	v_mov_b32_e32 v15, v6
	v_mov_b32_e32 v16, v6
	v_mov_b32_e32 v17, v6
	v_mov_b32_e32 v18, v6
	v_mov_b32_e32 v19, v6
	v_mov_b32_e32 v20, v6
	v_mov_b32_e32 v21, v6
	v_mov_b32_e32 v22, v6
	v_mov_b32_e32 v23, v6
	v_mov_b32_e32 v24, v6
	v_mov_b32_e32 v25, v6
	v_mov_b32_e32 v30, v6
	v_mov_b32_e32 v31, v6
	v_mov_b32_e32 v32, v6
	v_mov_b32_e32 v33, v6
	v_mov_b32_e32 v38, v6
	v_mov_b32_e32 v39, v6
	v_mov_b32_e32 v40, v6
	v_mov_b32_e32 v41, v6
	v_mov_b32_e32 v46, v6
	v_mov_b32_e32 v47, v6
	v_mov_b32_e32 v48, v6
	v_mov_b32_e32 v49, v6
	v_mov_b32_e32 v26, v6
	v_mov_b32_e32 v27, v6
	v_mov_b32_e32 v28, v6
	v_mov_b32_e32 v29, v6
	v_mov_b32_e32 v34, v6
	v_mov_b32_e32 v35, v6
	v_mov_b32_e32 v36, v6
	v_mov_b32_e32 v37, v6
	v_mov_b32_e32 v42, v6
	v_mov_b32_e32 v43, v6
	v_mov_b32_e32 v44, v6
	v_mov_b32_e32 v45, v6
	v_mov_b32_e32 v50, v6
	v_mov_b32_e32 v51, v6
	v_mov_b32_e32 v52, v6
	v_mov_b32_e32 v53, v6
	v_mov_b32_e32 v54, v6
	v_mov_b32_e32 v55, v6
	v_mov_b32_e32 v56, v6
	v_mov_b32_e32 v57, v6
	v_mov_b32_e32 v58, v6
	v_mov_b32_e32 v59, v6
	v_mov_b32_e32 v60, v6
	v_mov_b32_e32 v61, v6
	v_mov_b32_e32 v62, v6
	v_mov_b32_e32 v63, v6
	v_mov_b32_e32 v64, v6
	v_mov_b32_e32 v65, v6
	v_mov_b32_e32 v66, v6
	v_mov_b32_e32 v67, v6
	v_mov_b32_e32 v68, v6
	v_mov_b32_e32 v69, v6
	v_mov_b32_e32 v70, v6
	v_mov_b32_e32 v71, v6
	v_mov_b32_e32 v72, v6
	v_mov_b32_e32 v73, v6
	v_mov_b32_e32 v74, v6
	v_mov_b32_e32 v75, v6
	v_mov_b32_e32 v76, v6
	v_mov_b32_e32 v77, v6
	v_mov_b32_e32 v78, v6
	v_mov_b32_e32 v79, v6
	v_mov_b32_e32 v80, v6
	v_mov_b32_e32 v81, v6
	v_mov_b32_e32 v82, v6
	v_mov_b32_e32 v83, v6
	v_mov_b32_e32 v84, v6
	v_mov_b32_e32 v85, v6
	v_mov_b32_e32 v86, v6
	v_mov_b32_e32 v87, v6
	v_mov_b32_e32 v88, v6
	v_mov_b32_e32 v89, v6
	v_mov_b32_e32 v94, v6
	v_mov_b32_e32 v95, v6
	v_mov_b32_e32 v96, v6
	v_mov_b32_e32 v97, v6
	v_mov_b32_e32 v102, v6
	v_mov_b32_e32 v103, v6
	v_mov_b32_e32 v104, v6
	v_mov_b32_e32 v105, v6
	v_mov_b32_e32 v114, v6
	v_mov_b32_e32 v115, v6
	v_mov_b32_e32 v116, v6
	v_mov_b32_e32 v117, v6
	v_mov_b32_e32 v90, v6
	v_mov_b32_e32 v91, v6
	v_mov_b32_e32 v92, v6
	v_mov_b32_e32 v93, v6
	v_mov_b32_e32 v98, v6
	v_mov_b32_e32 v99, v6
	v_mov_b32_e32 v100, v6
	v_mov_b32_e32 v101, v6
	v_mov_b32_e32 v106, v6
	v_mov_b32_e32 v107, v6
	v_mov_b32_e32 v108, v6
	v_mov_b32_e32 v109, v6
	v_mov_b32_e32 v110, v6
	v_mov_b32_e32 v111, v6
	v_mov_b32_e32 v112, v6
	v_mov_b32_e32 v113, v6
	v_mov_b32_e32 v118, v6
	v_mov_b32_e32 v119, v6
	v_mov_b32_e32 v120, v6
	v_mov_b32_e32 v121, v6
	v_mov_b32_e32 v122, v6
	v_mov_b32_e32 v123, v6
	v_mov_b32_e32 v124, v6
	v_mov_b32_e32 v125, v6
	v_mov_b32_e32 v126, v6
	v_mov_b32_e32 v127, v6
	v_mov_b32_e32 v128, v6
	v_mov_b32_e32 v129, v6
	v_mov_b32_e32 v130, v6
	v_mov_b32_e32 v131, v6
	v_mov_b32_e32 v132, v6
	v_mov_b32_e32 v133, v6
	s_barrier
	s_branch .LBB0_270
	s_nop 0
	s_nop 0
	s_nop 0
	s_nop 0
	s_nop 0
	s_nop 0
	s_nop 0
	s_nop 0
	s_nop 0
.LBB0_268:
	s_mov_b64 s[22:23], s[24:25]
	s_mov_b64 s[4:5], s[20:21]
	s_mov_b32 s58, s59
	s_andn2_b64 vcc, exec, s[38:39]
	s_cbranch_vccz .LBB0_288
